# FFN-up SwiGLU epilogue rewritten: 8 interleaved exp/rcp chains per store group, no s_nop padding (same per-element op order)
# baseline (speedup 1.0000x reference)
.LBB0_170:
	v_lshl_or_b32 v150, s34, 7, v146
	v_lshl_add_u32 v148, s36, 8, v144
	v_ashrrev_i32_e32 v151, 31, v150
	v_mov_b64_e32 v[142:143], s[20:21]
	s_andn2_b64 vcc, exec, s[4:5]
	s_movk_i32 s65, 0xff5d
	s_movk_i32 s64, 0xff7c
	v_lshlrev_b64 v[152:153], 1, v[150:151]
	v_add_u32_e32 v192, 0, v148
	v_mul_f32_e32 v156, 0xbfb8aa3b, v126
	v_mul_f32_e32 v157, 0xbfb8aa3b, v127
	v_mul_f32_e32 v158, 0xbfb8aa3b, v128
	v_mul_f32_e32 v159, 0xbfb8aa3b, v129
	v_mul_f32_e32 v160, 0xbfb8aa3b, v118
	v_mul_f32_e32 v161, 0xbfb8aa3b, v119
	v_mul_f32_e32 v162, 0xbfb8aa3b, v120
	v_mul_f32_e32 v163, 0xbfb8aa3b, v121
	v_mad_i64_i32 v[188:189], s[34:35], v192, s47, v[142:143]
	v_exp_f32_e32 v156, v156
	v_exp_f32_e32 v157, v157
	v_exp_f32_e32 v158, v158
	v_exp_f32_e32 v159, v159
	v_exp_f32_e32 v160, v160
	v_exp_f32_e32 v161, v161
	v_exp_f32_e32 v162, v162
	v_exp_f32_e32 v163, v163
	v_lshl_add_u64 v[188:189], v[188:189], 0, v[152:153]
	v_add_f32_e32 v156, 1.0, v156
	v_add_f32_e32 v157, 1.0, v157
	v_add_f32_e32 v158, 1.0, v158
	v_add_f32_e32 v159, 1.0, v159
	v_add_f32_e32 v160, 1.0, v160
	v_add_f32_e32 v161, 1.0, v161
	v_add_f32_e32 v162, 1.0, v162
	v_add_f32_e32 v163, 1.0, v163
	v_rcp_f32_e32 v156, v156
	v_rcp_f32_e32 v157, v157
	v_rcp_f32_e32 v158, v158
	v_rcp_f32_e32 v159, v159
	v_rcp_f32_e32 v160, v160
	v_rcp_f32_e32 v161, v161
	v_rcp_f32_e32 v162, v162
	v_rcp_f32_e32 v163, v163
	v_mul_f32_e32 v156, v126, v156
	v_mul_f32_e32 v157, v127, v157
	v_mul_f32_e32 v158, v128, v158
	v_mul_f32_e32 v159, v129, v159
	v_mul_f32_e32 v160, v118, v160
	v_mul_f32_e32 v161, v119, v161
	v_mul_f32_e32 v162, v120, v162
	v_mul_f32_e32 v163, v121, v163
	v_mul_f32_e32 v156, v156, v122
	v_mul_f32_e32 v157, v157, v123
	v_mul_f32_e32 v158, v158, v124
	v_mul_f32_e32 v159, v159, v125
	v_mul_f32_e32 v160, v160, v114
	v_mul_f32_e32 v161, v161, v115
	v_mul_f32_e32 v162, v162, v116
	v_mul_f32_e32 v163, v163, v117
	v_cvt_pk_bf16_f32 v180, v156, v157
	v_cvt_pk_bf16_f32 v181, v158, v159
	v_cvt_pk_bf16_f32 v182, v160, v161
	v_cvt_pk_bf16_f32 v183, v162, v163
	global_store_dwordx4 v[188:189], v[180:183], off
	v_add_u32_e32 v193, 16, v148
	v_mul_f32_e32 v164, 0xbfb8aa3b, v110
	v_mul_f32_e32 v165, 0xbfb8aa3b, v111
	v_mul_f32_e32 v166, 0xbfb8aa3b, v112
	v_mul_f32_e32 v167, 0xbfb8aa3b, v113
	v_mul_f32_e32 v168, 0xbfb8aa3b, v102
	v_mul_f32_e32 v169, 0xbfb8aa3b, v103
	v_mul_f32_e32 v170, 0xbfb8aa3b, v104
	v_mul_f32_e32 v171, 0xbfb8aa3b, v105
	v_mad_i64_i32 v[190:191], s[34:35], v193, s47, v[142:143]
	v_exp_f32_e32 v164, v164
	v_exp_f32_e32 v165, v165
	v_exp_f32_e32 v166, v166
	v_exp_f32_e32 v167, v167
	v_exp_f32_e32 v168, v168
	v_exp_f32_e32 v169, v169
	v_exp_f32_e32 v170, v170
	v_exp_f32_e32 v171, v171
	v_lshl_add_u64 v[190:191], v[190:191], 0, v[152:153]
	v_add_f32_e32 v164, 1.0, v164
	v_add_f32_e32 v165, 1.0, v165
	v_add_f32_e32 v166, 1.0, v166
	v_add_f32_e32 v167, 1.0, v167
	v_add_f32_e32 v168, 1.0, v168
	v_add_f32_e32 v169, 1.0, v169
	v_add_f32_e32 v170, 1.0, v170
	v_add_f32_e32 v171, 1.0, v171
	v_rcp_f32_e32 v164, v164
	v_rcp_f32_e32 v165, v165
	v_rcp_f32_e32 v166, v166
	v_rcp_f32_e32 v167, v167
	v_rcp_f32_e32 v168, v168
	v_rcp_f32_e32 v169, v169
	v_rcp_f32_e32 v170, v170
	v_rcp_f32_e32 v171, v171
	v_mul_f32_e32 v164, v110, v164
	v_mul_f32_e32 v165, v111, v165
	v_mul_f32_e32 v166, v112, v166
	v_mul_f32_e32 v167, v113, v167
	v_mul_f32_e32 v168, v102, v168
	v_mul_f32_e32 v169, v103, v169
	v_mul_f32_e32 v170, v104, v170
	v_mul_f32_e32 v171, v105, v171
	v_mul_f32_e32 v164, v164, v106
	v_mul_f32_e32 v165, v165, v107
	v_mul_f32_e32 v166, v166, v108
	v_mul_f32_e32 v167, v167, v109
	v_mul_f32_e32 v168, v168, v98
	v_mul_f32_e32 v169, v169, v99
	v_mul_f32_e32 v170, v170, v100
	v_mul_f32_e32 v171, v171, v101
	v_cvt_pk_bf16_f32 v184, v164, v165
	v_cvt_pk_bf16_f32 v185, v166, v167
	v_cvt_pk_bf16_f32 v186, v168, v169
	v_cvt_pk_bf16_f32 v187, v170, v171
	global_store_dwordx4 v[190:191], v[184:187], off
	v_add_u32_e32 v192, 32, v148
	v_mul_f32_e32 v156, 0xbfb8aa3b, v94
	v_mul_f32_e32 v157, 0xbfb8aa3b, v95
	v_mul_f32_e32 v158, 0xbfb8aa3b, v96
	v_mul_f32_e32 v159, 0xbfb8aa3b, v97
	v_mul_f32_e32 v160, 0xbfb8aa3b, v86
	v_mul_f32_e32 v161, 0xbfb8aa3b, v87
	v_mul_f32_e32 v162, 0xbfb8aa3b, v88
	v_mul_f32_e32 v163, 0xbfb8aa3b, v89
	v_mad_i64_i32 v[188:189], s[34:35], v192, s47, v[142:143]
	v_exp_f32_e32 v156, v156
	v_exp_f32_e32 v157, v157
	v_exp_f32_e32 v158, v158
	v_exp_f32_e32 v159, v159
	v_exp_f32_e32 v160, v160
	v_exp_f32_e32 v161, v161
	v_exp_f32_e32 v162, v162
	v_exp_f32_e32 v163, v163
	v_lshl_add_u64 v[188:189], v[188:189], 0, v[152:153]
	v_add_f32_e32 v156, 1.0, v156
	v_add_f32_e32 v157, 1.0, v157
	v_add_f32_e32 v158, 1.0, v158
	v_add_f32_e32 v159, 1.0, v159
	v_add_f32_e32 v160, 1.0, v160
	v_add_f32_e32 v161, 1.0, v161
	v_add_f32_e32 v162, 1.0, v162
	v_add_f32_e32 v163, 1.0, v163
	v_rcp_f32_e32 v156, v156
	v_rcp_f32_e32 v157, v157
	v_rcp_f32_e32 v158, v158
	v_rcp_f32_e32 v159, v159
	v_rcp_f32_e32 v160, v160
	v_rcp_f32_e32 v161, v161
	v_rcp_f32_e32 v162, v162
	v_rcp_f32_e32 v163, v163
	v_mul_f32_e32 v156, v94, v156
	v_mul_f32_e32 v157, v95, v157
	v_mul_f32_e32 v158, v96, v158
	v_mul_f32_e32 v159, v97, v159
	v_mul_f32_e32 v160, v86, v160
	v_mul_f32_e32 v161, v87, v161
	v_mul_f32_e32 v162, v88, v162
	v_mul_f32_e32 v163, v89, v163
	v_mul_f32_e32 v156, v156, v90
	v_mul_f32_e32 v157, v157, v91
	v_mul_f32_e32 v158, v158, v92
	v_mul_f32_e32 v159, v159, v93
	v_mul_f32_e32 v160, v160, v82
	v_mul_f32_e32 v161, v161, v83
	v_mul_f32_e32 v162, v162, v84
	v_mul_f32_e32 v163, v163, v85
	v_cvt_pk_bf16_f32 v180, v156, v157
	v_cvt_pk_bf16_f32 v181, v158, v159
	v_cvt_pk_bf16_f32 v182, v160, v161
	v_cvt_pk_bf16_f32 v183, v162, v163
	global_store_dwordx4 v[188:189], v[180:183], off
	v_add_u32_e32 v193, 48, v148
	v_mul_f32_e32 v164, 0xbfb8aa3b, v78
	v_mul_f32_e32 v165, 0xbfb8aa3b, v79
	v_mul_f32_e32 v166, 0xbfb8aa3b, v80
	v_mul_f32_e32 v167, 0xbfb8aa3b, v81
	v_mul_f32_e32 v168, 0xbfb8aa3b, v70
	v_mul_f32_e32 v169, 0xbfb8aa3b, v71
	v_mul_f32_e32 v170, 0xbfb8aa3b, v72
	v_mul_f32_e32 v171, 0xbfb8aa3b, v73
	v_mad_i64_i32 v[190:191], s[34:35], v193, s47, v[142:143]
	v_exp_f32_e32 v164, v164
	v_exp_f32_e32 v165, v165
	v_exp_f32_e32 v166, v166
	v_exp_f32_e32 v167, v167
	v_exp_f32_e32 v168, v168
	v_exp_f32_e32 v169, v169
	v_exp_f32_e32 v170, v170
	v_exp_f32_e32 v171, v171
	v_lshl_add_u64 v[190:191], v[190:191], 0, v[152:153]
	v_add_f32_e32 v164, 1.0, v164
	v_add_f32_e32 v165, 1.0, v165
	v_add_f32_e32 v166, 1.0, v166
	v_add_f32_e32 v167, 1.0, v167
	v_add_f32_e32 v168, 1.0, v168
	v_add_f32_e32 v169, 1.0, v169
	v_add_f32_e32 v170, 1.0, v170
	v_add_f32_e32 v171, 1.0, v171
	v_rcp_f32_e32 v164, v164
	v_rcp_f32_e32 v165, v165
	v_rcp_f32_e32 v166, v166
	v_rcp_f32_e32 v167, v167
	v_rcp_f32_e32 v168, v168
	v_rcp_f32_e32 v169, v169
	v_rcp_f32_e32 v170, v170
	v_rcp_f32_e32 v171, v171
	v_mul_f32_e32 v164, v78, v164
	v_mul_f32_e32 v165, v79, v165
	v_mul_f32_e32 v166, v80, v166
	v_mul_f32_e32 v167, v81, v167
	v_mul_f32_e32 v168, v70, v168
	v_mul_f32_e32 v169, v71, v169
	v_mul_f32_e32 v170, v72, v170
	v_mul_f32_e32 v171, v73, v171
	v_mul_f32_e32 v164, v164, v74
	v_mul_f32_e32 v165, v165, v75
	v_mul_f32_e32 v166, v166, v76
	v_mul_f32_e32 v167, v167, v77
	v_mul_f32_e32 v168, v168, v66
	v_mul_f32_e32 v169, v169, v67
	v_mul_f32_e32 v170, v170, v68
	v_mul_f32_e32 v171, v171, v69
	v_cvt_pk_bf16_f32 v184, v164, v165
	v_cvt_pk_bf16_f32 v185, v166, v167
	v_cvt_pk_bf16_f32 v186, v168, v169
	v_cvt_pk_bf16_f32 v187, v170, v171
	global_store_dwordx4 v[190:191], v[184:187], off
	v_add_u32_e32 v192, 0x80, v148
	v_mul_f32_e32 v156, 0xbfb8aa3b, v62
	v_mul_f32_e32 v157, 0xbfb8aa3b, v63
	v_mul_f32_e32 v158, 0xbfb8aa3b, v64
	v_mul_f32_e32 v159, 0xbfb8aa3b, v65
	v_mul_f32_e32 v160, 0xbfb8aa3b, v54
	v_mul_f32_e32 v161, 0xbfb8aa3b, v55
	v_mul_f32_e32 v162, 0xbfb8aa3b, v56
	v_mul_f32_e32 v163, 0xbfb8aa3b, v57
	v_mad_i64_i32 v[188:189], s[34:35], v192, s47, v[142:143]
	v_exp_f32_e32 v156, v156
	v_exp_f32_e32 v157, v157
	v_exp_f32_e32 v158, v158
	v_exp_f32_e32 v159, v159
	v_exp_f32_e32 v160, v160
	v_exp_f32_e32 v161, v161
	v_exp_f32_e32 v162, v162
	v_exp_f32_e32 v163, v163
	v_lshl_add_u64 v[188:189], v[188:189], 0, v[152:153]
	v_add_f32_e32 v156, 1.0, v156
	v_add_f32_e32 v157, 1.0, v157
	v_add_f32_e32 v158, 1.0, v158
	v_add_f32_e32 v159, 1.0, v159
	v_add_f32_e32 v160, 1.0, v160
	v_add_f32_e32 v161, 1.0, v161
	v_add_f32_e32 v162, 1.0, v162
	v_add_f32_e32 v163, 1.0, v163
	v_rcp_f32_e32 v156, v156
	v_rcp_f32_e32 v157, v157
	v_rcp_f32_e32 v158, v158
	v_rcp_f32_e32 v159, v159
	v_rcp_f32_e32 v160, v160
	v_rcp_f32_e32 v161, v161
	v_rcp_f32_e32 v162, v162
	v_rcp_f32_e32 v163, v163
	v_mul_f32_e32 v156, v62, v156
	v_mul_f32_e32 v157, v63, v157
	v_mul_f32_e32 v158, v64, v158
	v_mul_f32_e32 v159, v65, v159
	v_mul_f32_e32 v160, v54, v160
	v_mul_f32_e32 v161, v55, v161
	v_mul_f32_e32 v162, v56, v162
	v_mul_f32_e32 v163, v57, v163
	v_mul_f32_e32 v156, v156, v58
	v_mul_f32_e32 v157, v157, v59
	v_mul_f32_e32 v158, v158, v60
	v_mul_f32_e32 v159, v159, v61
	v_mul_f32_e32 v160, v160, v50
	v_mul_f32_e32 v161, v161, v51
	v_mul_f32_e32 v162, v162, v52
	v_mul_f32_e32 v163, v163, v53
	v_cvt_pk_bf16_f32 v180, v156, v157
	v_cvt_pk_bf16_f32 v181, v158, v159
	v_cvt_pk_bf16_f32 v182, v160, v161
	v_cvt_pk_bf16_f32 v183, v162, v163
	global_store_dwordx4 v[188:189], v[180:183], off
	v_add_u32_e32 v193, 0x90, v148
	v_mul_f32_e32 v164, 0xbfb8aa3b, v46
	v_mul_f32_e32 v165, 0xbfb8aa3b, v47
	v_mul_f32_e32 v166, 0xbfb8aa3b, v48
	v_mul_f32_e32 v167, 0xbfb8aa3b, v49
	v_mul_f32_e32 v168, 0xbfb8aa3b, v38
	v_mul_f32_e32 v169, 0xbfb8aa3b, v39
	v_mul_f32_e32 v170, 0xbfb8aa3b, v40
	v_mul_f32_e32 v171, 0xbfb8aa3b, v41
	v_mad_i64_i32 v[190:191], s[34:35], v193, s47, v[142:143]
	v_exp_f32_e32 v164, v164
	v_exp_f32_e32 v165, v165
	v_exp_f32_e32 v166, v166
	v_exp_f32_e32 v167, v167
	v_exp_f32_e32 v168, v168
	v_exp_f32_e32 v169, v169
	v_exp_f32_e32 v170, v170
	v_exp_f32_e32 v171, v171
	v_lshl_add_u64 v[190:191], v[190:191], 0, v[152:153]
	v_add_f32_e32 v164, 1.0, v164
	v_add_f32_e32 v165, 1.0, v165
	v_add_f32_e32 v166, 1.0, v166
	v_add_f32_e32 v167, 1.0, v167
	v_add_f32_e32 v168, 1.0, v168
	v_add_f32_e32 v169, 1.0, v169
	v_add_f32_e32 v170, 1.0, v170
	v_add_f32_e32 v171, 1.0, v171
	v_rcp_f32_e32 v164, v164
	v_rcp_f32_e32 v165, v165
	v_rcp_f32_e32 v166, v166
	v_rcp_f32_e32 v167, v167
	v_rcp_f32_e32 v168, v168
	v_rcp_f32_e32 v169, v169
	v_rcp_f32_e32 v170, v170
	v_rcp_f32_e32 v171, v171
	v_mul_f32_e32 v164, v46, v164
	v_mul_f32_e32 v165, v47, v165
	v_mul_f32_e32 v166, v48, v166
	v_mul_f32_e32 v167, v49, v167
	v_mul_f32_e32 v168, v38, v168
	v_mul_f32_e32 v169, v39, v169
	v_mul_f32_e32 v170, v40, v170
	v_mul_f32_e32 v171, v41, v171
	v_mul_f32_e32 v164, v164, v42
	v_mul_f32_e32 v165, v165, v43
	v_mul_f32_e32 v166, v166, v44
	v_mul_f32_e32 v167, v167, v45
	v_mul_f32_e32 v168, v168, v34
	v_mul_f32_e32 v169, v169, v35
	v_mul_f32_e32 v170, v170, v36
	v_mul_f32_e32 v171, v171, v37
	v_cvt_pk_bf16_f32 v184, v164, v165
	v_cvt_pk_bf16_f32 v185, v166, v167
	v_cvt_pk_bf16_f32 v186, v168, v169
	v_cvt_pk_bf16_f32 v187, v170, v171
	global_store_dwordx4 v[190:191], v[184:187], off
	v_add_u32_e32 v192, 0xa0, v148
	v_mul_f32_e32 v156, 0xbfb8aa3b, v30
	v_mul_f32_e32 v157, 0xbfb8aa3b, v31
	v_mul_f32_e32 v158, 0xbfb8aa3b, v32
	v_mul_f32_e32 v159, 0xbfb8aa3b, v33
	v_mul_f32_e32 v160, 0xbfb8aa3b, v22
	v_mul_f32_e32 v161, 0xbfb8aa3b, v23
	v_mul_f32_e32 v162, 0xbfb8aa3b, v24
	v_mul_f32_e32 v163, 0xbfb8aa3b, v25
	v_mad_i64_i32 v[188:189], s[34:35], v192, s47, v[142:143]
	v_exp_f32_e32 v156, v156
	v_exp_f32_e32 v157, v157
	v_exp_f32_e32 v158, v158
	v_exp_f32_e32 v159, v159
	v_exp_f32_e32 v160, v160
	v_exp_f32_e32 v161, v161
	v_exp_f32_e32 v162, v162
	v_exp_f32_e32 v163, v163
	v_lshl_add_u64 v[188:189], v[188:189], 0, v[152:153]
	v_add_f32_e32 v156, 1.0, v156
	v_add_f32_e32 v157, 1.0, v157
	v_add_f32_e32 v158, 1.0, v158
	v_add_f32_e32 v159, 1.0, v159
	v_add_f32_e32 v160, 1.0, v160
	v_add_f32_e32 v161, 1.0, v161
	v_add_f32_e32 v162, 1.0, v162
	v_add_f32_e32 v163, 1.0, v163
	v_rcp_f32_e32 v156, v156
	v_rcp_f32_e32 v157, v157
	v_rcp_f32_e32 v158, v158
	v_rcp_f32_e32 v159, v159
	v_rcp_f32_e32 v160, v160
	v_rcp_f32_e32 v161, v161
	v_rcp_f32_e32 v162, v162
	v_rcp_f32_e32 v163, v163
	v_mul_f32_e32 v156, v30, v156
	v_mul_f32_e32 v157, v31, v157
	v_mul_f32_e32 v158, v32, v158
	v_mul_f32_e32 v159, v33, v159
	v_mul_f32_e32 v160, v22, v160
	v_mul_f32_e32 v161, v23, v161
	v_mul_f32_e32 v162, v24, v162
	v_mul_f32_e32 v163, v25, v163
	v_mul_f32_e32 v156, v156, v26
	v_mul_f32_e32 v157, v157, v27
	v_mul_f32_e32 v158, v158, v28
	v_mul_f32_e32 v159, v159, v29
	v_mul_f32_e32 v160, v160, v18
	v_mul_f32_e32 v161, v161, v19
	v_mul_f32_e32 v162, v162, v20
	v_mul_f32_e32 v163, v163, v21
	v_cvt_pk_bf16_f32 v180, v156, v157
	v_cvt_pk_bf16_f32 v181, v158, v159
	v_cvt_pk_bf16_f32 v182, v160, v161
	v_cvt_pk_bf16_f32 v183, v162, v163
	global_store_dwordx4 v[188:189], v[180:183], off
	v_add_u32_e32 v193, 0xb0, v148
	v_mul_f32_e32 v164, 0xbfb8aa3b, v14
	v_mul_f32_e32 v165, 0xbfb8aa3b, v15
	v_mul_f32_e32 v166, 0xbfb8aa3b, v16
	v_mul_f32_e32 v167, 0xbfb8aa3b, v17
	v_mul_f32_e32 v168, 0xbfb8aa3b, v6
	v_mul_f32_e32 v169, 0xbfb8aa3b, v7
	v_mul_f32_e32 v170, 0xbfb8aa3b, v8
	v_mul_f32_e32 v171, 0xbfb8aa3b, v9
	v_mad_i64_i32 v[190:191], s[34:35], v193, s47, v[142:143]
	v_exp_f32_e32 v164, v164
	v_exp_f32_e32 v165, v165
	v_exp_f32_e32 v166, v166
	v_exp_f32_e32 v167, v167
	v_exp_f32_e32 v168, v168
	v_exp_f32_e32 v169, v169
	v_exp_f32_e32 v170, v170
	v_exp_f32_e32 v171, v171
	v_lshl_add_u64 v[190:191], v[190:191], 0, v[152:153]
	v_add_f32_e32 v164, 1.0, v164
	v_add_f32_e32 v165, 1.0, v165
	v_add_f32_e32 v166, 1.0, v166
	v_add_f32_e32 v167, 1.0, v167
	v_add_f32_e32 v168, 1.0, v168
	v_add_f32_e32 v169, 1.0, v169
	v_add_f32_e32 v170, 1.0, v170
	v_add_f32_e32 v171, 1.0, v171
	v_rcp_f32_e32 v164, v164
	v_rcp_f32_e32 v165, v165
	v_rcp_f32_e32 v166, v166
	v_rcp_f32_e32 v167, v167
	v_rcp_f32_e32 v168, v168
	v_rcp_f32_e32 v169, v169
	v_rcp_f32_e32 v170, v170
	v_rcp_f32_e32 v171, v171
	v_mul_f32_e32 v164, v14, v164
	v_mul_f32_e32 v165, v15, v165
	v_mul_f32_e32 v166, v16, v166
	v_mul_f32_e32 v167, v17, v167
	v_mul_f32_e32 v168, v6, v168
	v_mul_f32_e32 v169, v7, v169
	v_mul_f32_e32 v170, v8, v170
	v_mul_f32_e32 v171, v9, v171
	v_mul_f32_e32 v164, v164, v10
	v_mul_f32_e32 v165, v165, v11
	v_mul_f32_e32 v166, v166, v12
	v_mul_f32_e32 v167, v167, v13
	v_mul_f32_e32 v168, v168, v2
	v_mul_f32_e32 v169, v169, v3
	v_mul_f32_e32 v170, v170, v4
	v_mul_f32_e32 v171, v171, v5
	v_cvt_pk_bf16_f32 v184, v164, v165
	v_cvt_pk_bf16_f32 v185, v166, v167
	v_cvt_pk_bf16_f32 v186, v168, v169
	v_cvt_pk_bf16_f32 v187, v170, v171
	global_store_dwordx4 v[190:191], v[184:187], off
	s_mov_b64 s[34:35], -1
	s_cbranch_vccnz .LBB0_163
	s_andn2_b64 vcc, exec, s[12:13]
	s_cbranch_vccnz .LBB0_162
	s_barrier
	s_branch .LBB0_162
